# grid seams: L1 invalidate issued while waiting for the release (early buffer_inv), not after observing it
# speedup vs baseline: 1.0230x; 1.0164x over previous
.LBB0_176:
	s_or_b64 exec, exec, s[14:15]
	v_cvt_f32_u32_e32 v4, v2
	s_waitcnt vmcnt(0)
	v_readfirstlane_b32 s12, v3
	v_sub_u32_e32 v3, 0, v2
	v_rcp_iflag_f32_e32 v4, v4
	v_add_u32_e32 v5, s12, v1
	v_mul_f32_e32 v4, 0x4f7ffffe, v4
	v_cvt_u32_f32_e32 v4, v4
	v_mul_lo_u32 v1, v3, v4
	v_mul_hi_u32 v1, v4, v1
	v_add_u32_e32 v1, v4, v1
	v_mul_hi_u32 v1, v5, v1
	v_mul_lo_u32 v3, v1, v2
	v_sub_u32_e32 v3, v5, v3
	v_add_u32_e32 v4, 1, v1
	v_cmp_ge_u32_e32 vcc, v3, v2
	s_nop 1
	v_cndmask_b32_e32 v1, v1, v4, vcc
	v_sub_u32_e32 v4, v3, v2
	v_cndmask_b32_e32 v3, v3, v4, vcc
	v_add_u32_e32 v4, 1, v1
	v_cmp_ge_u32_e32 vcc, v3, v2
	v_add_u32_e32 v3, 1, v5
	s_nop 0
	v_cndmask_b32_e32 v1, v1, v4, vcc
	v_mul_lo_u32 v4, v2, v1
	v_add_u32_e32 v2, v4, v2
	v_cmp_ne_u32_e32 vcc, v3, v2
	s_and_saveexec_b64 s[12:13], vcc
	s_xor_b64 s[12:13], exec, s[12:13]
	s_cbranch_execz .LBB0_190
	s_waitcnt lgkmcnt(0)
	v_mov_b32_e32 v0, 0x2000
	buffer_inv sc1
	global_load_dword v0, v0, s[6:7] offset:1024 sc1
	s_add_u32 s18, s6, 0x2400
	s_addc_u32 s19, s7, 0
	s_waitcnt vmcnt(0)
	v_cmp_eq_u32_e32 vcc, v0, v1
	s_and_saveexec_b64 s[14:15], vcc
	s_cbranch_execz .LBB0_189
	s_add_u32 s16, s10, 0x1200
	s_addc_u32 s17, s11, 0
	s_mov_b32 s34, 1
	s_mov_b64 s[20:21], 0
	v_mov_b32_e32 v0, 0
	s_branch .LBB0_180

.LBB0_189:
	s_or_b64 exec, exec, s[14:15]
	s_waitcnt vmcnt(0)
	s_waitcnt vmcnt(0)

.LBB0_193:
	s_or_b64 exec, exec, s[14:15]
	buffer_inv sc1
	v_cvt_f32_u32_e32 v3, v0
	s_waitcnt vmcnt(1)
	v_readfirstlane_b32 s12, v2
	s_add_u32 s14, s10, 0x4500
	s_addc_u32 s15, s11, 0
	v_rcp_iflag_f32_e32 v3, v3
	v_add_u32_e32 v1, s12, v1
	v_add_u32_e32 v4, 1, v1
	s_mov_b64 s[16:17], -1
	v_mul_f32_e32 v2, 0x4f7ffffe, v3
	v_cvt_u32_f32_e32 v2, v2
	v_sub_u32_e32 v3, 0, v0
	v_mul_lo_u32 v3, v3, v2
	v_mul_hi_u32 v3, v2, v3
	v_add_u32_e32 v2, v2, v3
	v_mul_hi_u32 v2, v1, v2
	v_mul_lo_u32 v3, v2, v0
	v_sub_u32_e32 v1, v1, v3
	v_add_u32_e32 v5, 1, v2
	v_cmp_ge_u32_e32 vcc, v1, v0
	v_sub_u32_e32 v3, v1, v0
	s_nop 0
	v_cndmask_b32_e32 v2, v2, v5, vcc
	v_cndmask_b32_e32 v1, v1, v3, vcc
	v_add_u32_e32 v3, 1, v2
	v_cmp_ge_u32_e32 vcc, v1, v0
	s_nop 1
	v_cndmask_b32_e32 v2, v2, v3, vcc
	v_mul_lo_u32 v1, v0, v2
	v_add_u32_e32 v0, v1, v0
	v_cmp_ne_u32_e32 vcc, v4, v0
	v_mov_b64_e32 v[0:1], s[14:15]
	s_and_saveexec_b64 s[12:13], vcc
	s_cbranch_execz .LBB0_205
	v_mov_b32_e32 v0, 0
	global_load_dword v1, v0, s[14:15] sc1
	s_mov_b64 s[20:21], 0
	s_waitcnt vmcnt(0)
	v_cmp_eq_u32_e32 vcc, v1, v2
	s_and_saveexec_b64 s[18:19], vcc
	s_cbranch_execz .LBB0_204
	s_add_u32 s16, s10, 0x1200
	s_addc_u32 s17, s11, 0
	s_mov_b32 s30, 1
	s_mov_b64 s[10:11], 0
	s_branch .LBB0_197

.LBB0_207:
	s_or_b64 exec, exec, s[10:11]
	s_mov_b64 s[10:11], exec
	v_mbcnt_lo_u32_b32 v0, s10, 0
	v_mbcnt_hi_u32_b32 v0, s11, v0
	v_cmp_eq_u32_e32 vcc, 0, v0
	s_and_saveexec_b64 s[12:13], vcc
	s_cbranch_execz .LBB0_209
	s_bcnt1_i32_b64 s10, s[10:11]
	v_mov_b32_e32 v0, 0x2000
	v_mov_b32_e32 v1, s10
	global_atomic_add v0, v1, s[6:7] offset:1024

.LBB0_283:
	s_or_b64 exec, exec, s[14:15]
	v_cvt_f32_u32_e32 v4, v2
	s_waitcnt vmcnt(0)
	v_readfirstlane_b32 s12, v3
	v_sub_u32_e32 v3, 0, v2
	v_rcp_iflag_f32_e32 v4, v4
	v_add_u32_e32 v5, s12, v1
	v_mul_f32_e32 v4, 0x4f7ffffe, v4
	v_cvt_u32_f32_e32 v4, v4
	v_mul_lo_u32 v1, v3, v4
	v_mul_hi_u32 v1, v4, v1
	v_add_u32_e32 v1, v4, v1
	v_mul_hi_u32 v1, v5, v1
	v_mul_lo_u32 v3, v1, v2
	v_sub_u32_e32 v3, v5, v3
	v_add_u32_e32 v4, 1, v1
	v_cmp_ge_u32_e32 vcc, v3, v2
	s_nop 1
	v_cndmask_b32_e32 v1, v1, v4, vcc
	v_sub_u32_e32 v4, v3, v2
	v_cndmask_b32_e32 v3, v3, v4, vcc
	v_add_u32_e32 v4, 1, v1
	v_cmp_ge_u32_e32 vcc, v3, v2
	v_add_u32_e32 v3, 1, v5
	s_nop 0
	v_cndmask_b32_e32 v1, v1, v4, vcc
	v_mul_lo_u32 v4, v2, v1
	v_add_u32_e32 v2, v4, v2
	v_cmp_ne_u32_e32 vcc, v3, v2
	s_and_saveexec_b64 s[12:13], vcc
	s_xor_b64 s[12:13], exec, s[12:13]
	s_cbranch_execz .LBB0_297
	s_waitcnt lgkmcnt(0)
	v_mov_b32_e32 v0, 0x2000
	buffer_inv sc1
	global_load_dword v0, v0, s[10:11] offset:1024 sc1
	s_add_u32 s18, s10, 0x2400
	s_addc_u32 s19, s11, 0
	s_waitcnt vmcnt(0)
	v_cmp_eq_u32_e32 vcc, v0, v1
	s_and_saveexec_b64 s[14:15], vcc
	s_cbranch_execz .LBB0_296
	s_add_u32 s16, s6, 0x1200
	s_addc_u32 s17, s7, 0
	s_mov_b32 s26, 1
	s_mov_b64 s[20:21], 0
	s_branch .LBB0_287

.LBB0_300:
	s_or_b64 exec, exec, s[14:15]
	buffer_inv sc1
	v_cvt_f32_u32_e32 v3, v0
	s_waitcnt vmcnt(1)
	v_readfirstlane_b32 s12, v2
	s_mov_b64 s[16:17], -1
	v_rcp_iflag_f32_e32 v3, v3
	v_add_u32_e32 v1, s12, v1
	v_add_u32_e32 v4, 1, v1
	s_add_u32 s12, s6, 0x4500
	v_mul_f32_e32 v2, 0x4f7ffffe, v3
	v_cvt_u32_f32_e32 v2, v2
	v_sub_u32_e32 v3, 0, v0
	s_addc_u32 s13, s7, 0
	v_mul_lo_u32 v3, v3, v2
	v_mul_hi_u32 v3, v2, v3
	v_add_u32_e32 v2, v2, v3
	v_mul_hi_u32 v2, v1, v2
	v_mul_lo_u32 v3, v2, v0
	v_sub_u32_e32 v1, v1, v3
	v_add_u32_e32 v5, 1, v2
	v_cmp_ge_u32_e32 vcc, v1, v0
	v_sub_u32_e32 v3, v1, v0
	s_nop 0
	v_cndmask_b32_e32 v2, v2, v5, vcc
	v_cndmask_b32_e32 v1, v1, v3, vcc
	v_add_u32_e32 v3, 1, v2
	v_cmp_ge_u32_e32 vcc, v1, v0
	s_nop 1
	v_cndmask_b32_e32 v2, v2, v3, vcc
	v_mul_lo_u32 v1, v0, v2
	v_add_u32_e32 v0, v1, v0
	v_cmp_ne_u32_e32 vcc, v4, v0
	v_mov_b64_e32 v[0:1], s[12:13]
	s_and_saveexec_b64 s[14:15], vcc
	s_cbranch_execz .LBB0_312
	global_load_dword v0, v169, s[12:13] sc1
	s_mov_b64 s[20:21], 0
	s_waitcnt vmcnt(0)
	v_cmp_eq_u32_e32 vcc, v0, v2
	s_and_saveexec_b64 s[18:19], vcc
	s_cbranch_execz .LBB0_311
	s_add_u32 s16, s6, 0x1200
	s_addc_u32 s17, s7, 0
	s_mov_b32 s26, 1
	s_mov_b64 s[6:7], 0
	s_branch .LBB0_304

.LBB0_314:
	s_or_b64 exec, exec, s[6:7]
	s_mov_b64 s[6:7], exec
	v_mbcnt_lo_u32_b32 v0, s6, 0
	v_mbcnt_hi_u32_b32 v0, s7, v0
	v_cmp_eq_u32_e32 vcc, 0, v0
	s_and_saveexec_b64 s[12:13], vcc
	s_cbranch_execz .LBB0_316
	s_bcnt1_i32_b64 s6, s[6:7]
	v_mov_b32_e32 v0, s6
	v_mov_b32_e32 v1, 0x2000
	global_atomic_add v1, v0, s[10:11] offset:1024

.LBB0_798:
	s_or_b64 exec, exec, s[16:17]
	s_waitcnt vmcnt(0)
	s_waitcnt vmcnt(0)

.LBB0_802:
	s_or_b64 exec, exec, s[16:17]
	buffer_inv sc1
	v_cvt_f32_u32_e32 v3, v0
	s_waitcnt vmcnt(1)
	v_readfirstlane_b32 s14, v2
	s_mov_b64 s[18:19], -1
	v_rcp_iflag_f32_e32 v3, v3
	v_add_u32_e32 v1, s14, v1
	v_add_u32_e32 v4, 1, v1
	s_add_u32 s14, s6, 0x4500
	v_mul_f32_e32 v2, 0x4f7ffffe, v3
	v_cvt_u32_f32_e32 v2, v2
	v_sub_u32_e32 v3, 0, v0
	s_addc_u32 s15, s7, 0
	v_mul_lo_u32 v3, v3, v2
	v_mul_hi_u32 v3, v2, v3
	v_add_u32_e32 v2, v2, v3
	v_mul_hi_u32 v2, v1, v2
	v_mul_lo_u32 v3, v2, v0
	v_sub_u32_e32 v1, v1, v3
	v_add_u32_e32 v5, 1, v2
	v_cmp_ge_u32_e32 vcc, v1, v0
	v_sub_u32_e32 v3, v1, v0
	s_nop 0
	v_cndmask_b32_e32 v2, v2, v5, vcc
	v_cndmask_b32_e32 v1, v1, v3, vcc
	v_add_u32_e32 v3, 1, v2
	v_cmp_ge_u32_e32 vcc, v1, v0
	s_nop 1
	v_cndmask_b32_e32 v2, v2, v3, vcc
	v_mul_lo_u32 v1, v0, v2
	v_add_u32_e32 v0, v1, v0
	v_cmp_ne_u32_e32 vcc, v4, v0
	v_mov_b64_e32 v[0:1], s[14:15]
	s_and_saveexec_b64 s[16:17], vcc
	s_cbranch_execz .LBB0_814
	global_load_dword v0, v169, s[14:15] sc1
	s_mov_b64 s[22:23], 0
	s_waitcnt vmcnt(0)
	v_cmp_eq_u32_e32 vcc, v0, v2
	s_and_saveexec_b64 s[20:21], vcc
	s_cbranch_execz .LBB0_813
	s_add_u32 s18, s6, 0x1200
	s_addc_u32 s19, s7, 0
	s_mov_b32 s26, 1
	s_mov_b64 s[6:7], 0
	s_branch .LBB0_806

.LBB0_816:
	s_or_b64 exec, exec, s[6:7]
	s_mov_b64 s[6:7], exec
	v_mbcnt_lo_u32_b32 v0, s6, 0
	v_mbcnt_hi_u32_b32 v0, s7, v0
	v_cmp_eq_u32_e32 vcc, 0, v0
	s_and_saveexec_b64 s[14:15], vcc
	s_cbranch_execz .LBB0_818
	s_bcnt1_i32_b64 s6, s[6:7]
	v_mov_b32_e32 v0, s6
	v_mov_b32_e32 v1, 0x2000
	global_atomic_add v1, v0, s[12:13] offset:1024

.LBB0_949:
	s_or_b64 exec, exec, s[6:7]
	s_mov_b64 s[6:7], exec
	v_mbcnt_lo_u32_b32 v0, s6, 0
	v_mbcnt_hi_u32_b32 v0, s7, v0
	v_cmp_eq_u32_e32 vcc, 0, v0
	s_and_saveexec_b64 s[12:13], vcc
	s_cbranch_execz .LBB0_211
	s_bcnt1_i32_b64 s6, s[6:7]
	v_mov_b32_e32 v0, s6
	v_mov_b32_e32 v1, 0x2000
	global_atomic_add v1, v0, s[10:11] offset:1024
	s_branch .LBB0_211
